# also removed the L1 invalidate of the 4 four-owner panel syncs (data is write-through and never L1-resident in that phase)
# speedup vs baseline: 1.0019x; 1.0019x over previous
; __device__ __forceinline__ void panel_sync(unsigned* w) {
;     asm volatile("s_waitcnt vmcnt(0)" ::: "memory"); __syncthreads();
;     if (threadIdx.x == 0) { __hip_atomic_fetch_add(w, 1u, __ATOMIC_RELAXED, __HIP_MEMORY_SCOPE_AGENT); unsigned sp = 0;
;         while (__hip_atomic_load(w, __ATOMIC_RELAXED, __HIP_MEMORY_SCOPE_AGENT) < 4u) { __builtin_amdgcn_s_sleep(1); if (++sp > (1u << 22)) break; }
;         __builtin_amdgcn_fence(__ATOMIC_ACQUIRE, "agent"); asm volatile("s_waitcnt vmcnt(0)" ::: "memory"); }
;     __syncthreads();
; }
.LBB0_648:
.LBB0_649:
	s_or_b64 exec, exec, s[2:3]
	s_barrier

; __device__ __forceinline__ void panel_sync(unsigned* w) {
;     asm volatile("s_waitcnt vmcnt(0)" ::: "memory"); __syncthreads();
;     if (threadIdx.x == 0) { __hip_atomic_fetch_add(w, 1u, __ATOMIC_RELAXED, __HIP_MEMORY_SCOPE_AGENT); unsigned sp = 0;
;         while (__hip_atomic_load(w, __ATOMIC_RELAXED, __HIP_MEMORY_SCOPE_AGENT) < 4u) { __builtin_amdgcn_s_sleep(1); if (++sp > (1u << 22)) break; }
;         __builtin_amdgcn_fence(__ATOMIC_ACQUIRE, "agent"); asm volatile("s_waitcnt vmcnt(0)" ::: "memory"); }
;     __syncthreads();
; }
.LBB0_864:
.LBB0_865:
	s_or_b64 exec, exec, s[4:5]
	s_barrier
